# attention V staging loads hoisted, init_rows param loads hoisted, grid barrier L1 invalidate issued early (overlaps the wait)
# speedup vs baseline: 1.0121x; 1.0121x over previous
.LBB0_103:
	s_or_b64 exec, exec, s[14:15]
	v_cvt_f32_u32_e32 v4, v2
	s_waitcnt vmcnt(0)
	buffer_inv sc1
	v_readfirstlane_b32 s12, v3
	v_sub_u32_e32 v3, 0, v2
	v_rcp_iflag_f32_e32 v4, v4
	v_add_u32_e32 v5, s12, v1
	v_mul_f32_e32 v4, 0x4f7ffffe, v4
	v_cvt_u32_f32_e32 v4, v4
	v_mul_lo_u32 v1, v3, v4
	v_mul_hi_u32 v1, v4, v1
	v_add_u32_e32 v1, v4, v1
	v_mul_hi_u32 v1, v5, v1
	v_mul_lo_u32 v3, v1, v2
	v_sub_u32_e32 v3, v5, v3
	v_add_u32_e32 v4, 1, v1
	v_cmp_ge_u32_e32 vcc, v3, v2
	s_nop 1
	v_cndmask_b32_e32 v1, v1, v4, vcc
	v_sub_u32_e32 v4, v3, v2
	v_cndmask_b32_e32 v3, v3, v4, vcc
	v_add_u32_e32 v4, 1, v1
	v_cmp_ge_u32_e32 vcc, v3, v2
	v_add_u32_e32 v3, 1, v5
	s_nop 0
	v_cndmask_b32_e32 v1, v1, v4, vcc
	v_mul_lo_u32 v4, v2, v1
	v_add_u32_e32 v2, v4, v2
	v_cmp_ne_u32_e32 vcc, v3, v2
	s_and_saveexec_b64 s[12:13], vcc
	s_xor_b64 s[12:13], exec, s[12:13]
	s_cbranch_execz .LBB0_117
	s_waitcnt lgkmcnt(0)
	global_load_dword v0, v234, s[10:11] offset:1024 sc1
	s_add_u32 s18, s10, 0x2400
	s_addc_u32 s19, s11, 0
	s_waitcnt vmcnt(0)
	v_cmp_eq_u32_e32 vcc, v0, v1
	s_and_saveexec_b64 s[14:15], vcc
	s_cbranch_execz .LBB0_116
	s_add_u32 s16, s8, 0x1b069200
	s_addc_u32 s17, s9, 0
	s_mov_b32 s30, 1
	s_mov_b64 s[20:21], 0
	s_branch .LBB0_107

.LBB0_116:
	s_or_b64 exec, exec, s[14:15]
	s_waitcnt vmcnt(0)
	s_waitcnt vmcnt(0)

.LBB0_134:
	s_or_b64 exec, exec, s[8:9]
	s_mov_b64 s[8:9], exec
	v_mbcnt_lo_u32_b32 v0, s8, 0
	v_mbcnt_hi_u32_b32 v0, s9, v0
	v_cmp_eq_u32_e32 vcc, 0, v0
	s_waitcnt vmcnt(0)
	s_and_saveexec_b64 s[12:13], vcc
	s_cbranch_execz .LBB0_136
	s_bcnt1_i32_b64 s8, s[8:9]
	v_mov_b32_e32 v0, s8
	global_atomic_add v234, v0, s[10:11] offset:1024

.LBB0_164:
	s_or_b64 exec, exec, s[46:47]
	v_add_u32_e32 v0, s51, v117
	v_cmp_lt_i32_e64 s[46:47], -1, v0
	s_ashr_i32 s7, s6, 31
	s_lshl_b64 s[6:7], s[6:7], 12
	v_cndmask_b32_e64 v0, 0, v0, s[46:47]
	v_ashrrev_i32_e32 v1, 31, v0
	v_lshl_add_u64 v[0:1], s[6:7], 0, v[0:1]
	v_lshlrev_b64 v[0:1], 11, v[0:1]
	v_lshl_add_u64 v[0:1], s[60:61], 0, v[0:1]
	v_lshl_add_u64 v[0:1], v[24:25], 2, v[0:1]
	v_lshl_add_u64 v[6:7], v[96:97], 2, v[0:1]
	v_add_u32_e32 v0, v118, v26
	v_ashrrev_i32_e32 v1, 31, v0
	v_lshlrev_b64 v[4:5], 10, v[0:1]
	global_load_dwordx4 v[176:179], v[6:7], off offset:1024
	global_load_dwordx4 v[180:183], v[6:7], off offset:1040
	global_load_dwordx4 v[184:187], v[6:7], off offset:1056
	global_load_dwordx4 v[188:191], v[6:7], off offset:1072
	global_load_dwordx4 v[196:199], v[6:7], off offset:1088
	global_load_dwordx4 v[200:203], v[6:7], off offset:1104
	global_load_dwordx4 v[204:207], v[6:7], off offset:1120
	global_load_dwordx4 v[208:211], v[6:7], off offset:1136
	v_readlane_b32 s48, v255, 7
	v_readlane_b32 s49, v255, 8
	s_and_b64 s[8:9], s[8:9], s[48:49]
	s_waitcnt vmcnt(7)
	v_cndmask_b32_e64 v176, 0, v176, s[46:47]
	v_bfe_u32 v8, v176, 16, 1
	v_cndmask_b32_e64 v177, 0, v177, s[46:47]
	v_add3_u32 v8, v176, v8, s53
	ds_write_b16_d16_hi v126, v8 offset:36864
	v_bfe_u32 v8, v177, 16, 1
	v_cndmask_b32_e64 v178, 0, v178, s[46:47]
	v_add3_u32 v8, v177, v8, s53
	ds_write_b16_d16_hi v126, v8 offset:37384
	v_bfe_u32 v8, v178, 16, 1
	v_cndmask_b32_e64 v179, 0, v179, s[46:47]
	v_add3_u32 v8, v178, v8, s53
	ds_write_b16_d16_hi v126, v8 offset:37904
	v_bfe_u32 v8, v179, 16, 1
	v_add3_u32 v8, v179, v8, s53
	ds_write_b16_d16_hi v126, v8 offset:38424
	s_and_saveexec_b64 s[48:49], s[8:9]
	s_cbranch_execz .LBB0_166
	s_load_dwordx2 s[54:55], s[0:1], 0xd0
	s_waitcnt lgkmcnt(0)
	v_lshl_add_u64 v[8:9], s[54:55], 0, v[4:5]
	v_lshl_add_u64 v[8:9], v[24:25], 2, v[8:9]
	v_lshl_add_u64 v[8:9], v[96:97], 2, v[8:9]
	v_add_co_u32_e32 v8, vcc, 0x4500000, v8
	s_nop 1
	v_addc_co_u32_e32 v9, vcc, 0, v9, vcc
	global_store_dwordx4 v[8:9], v[176:179], off
.LBB0_166:
	s_or_b64 exec, exec, s[48:49]
	s_waitcnt vmcnt(6)
	v_cndmask_b32_e64 v180, 0, v180, s[46:47]
	v_bfe_u32 v8, v180, 16, 1
	v_cndmask_b32_e64 v181, 0, v181, s[46:47]
	v_add3_u32 v8, v180, v8, s53
	ds_write_b16_d16_hi v126, v8 offset:38944
	v_bfe_u32 v8, v181, 16, 1
	v_cndmask_b32_e64 v182, 0, v182, s[46:47]
	v_add3_u32 v8, v181, v8, s53
	ds_write_b16_d16_hi v126, v8 offset:39464
	v_bfe_u32 v8, v182, 16, 1
	v_cndmask_b32_e64 v183, 0, v183, s[46:47]
	v_add3_u32 v8, v182, v8, s53
	ds_write_b16_d16_hi v126, v8 offset:39984
	v_bfe_u32 v8, v183, 16, 1
	v_add3_u32 v8, v183, v8, s53
	ds_write_b16_d16_hi v126, v8 offset:40504
	s_and_saveexec_b64 s[48:49], s[8:9]
	s_cbranch_execz .LBB0_168
	s_load_dwordx2 s[54:55], s[0:1], 0xd0
	s_waitcnt lgkmcnt(0)
	v_lshl_add_u64 v[8:9], s[54:55], 0, v[4:5]
	v_lshl_add_u64 v[8:9], v[24:25], 2, v[8:9]
	v_lshl_add_u64 v[8:9], v[96:97], 2, v[8:9]
	v_add_co_u32_e32 v8, vcc, 0x4500000, v8
	s_nop 1
	v_addc_co_u32_e32 v9, vcc, 0, v9, vcc
	global_store_dwordx4 v[8:9], v[180:183], off offset:16
.LBB0_168:
	s_or_b64 exec, exec, s[48:49]
	s_waitcnt vmcnt(5)
	v_cndmask_b32_e64 v184, 0, v184, s[46:47]
	v_bfe_u32 v8, v184, 16, 1
	v_cndmask_b32_e64 v185, 0, v185, s[46:47]
	v_add3_u32 v8, v184, v8, s53
	ds_write_b16_d16_hi v126, v8 offset:41024
	v_bfe_u32 v8, v185, 16, 1
	v_cndmask_b32_e64 v186, 0, v186, s[46:47]
	v_add3_u32 v8, v185, v8, s53
	ds_write_b16_d16_hi v126, v8 offset:41544
	v_bfe_u32 v8, v186, 16, 1
	v_cndmask_b32_e64 v187, 0, v187, s[46:47]
	v_add3_u32 v8, v186, v8, s53
	ds_write_b16_d16_hi v126, v8 offset:42064
	v_bfe_u32 v8, v187, 16, 1
	v_add3_u32 v8, v187, v8, s53
	ds_write_b16_d16_hi v126, v8 offset:42584
	s_and_saveexec_b64 s[48:49], s[8:9]
	s_cbranch_execz .LBB0_170
	s_load_dwordx2 s[54:55], s[0:1], 0xd0
	s_waitcnt lgkmcnt(0)
	v_lshl_add_u64 v[8:9], s[54:55], 0, v[4:5]
	v_lshl_add_u64 v[8:9], v[24:25], 2, v[8:9]
	v_lshl_add_u64 v[8:9], v[96:97], 2, v[8:9]
	v_add_co_u32_e32 v8, vcc, 0x4500000, v8
	s_nop 1
	v_addc_co_u32_e32 v9, vcc, 0, v9, vcc
	global_store_dwordx4 v[8:9], v[184:187], off offset:32
.LBB0_170:
	s_or_b64 exec, exec, s[48:49]
	s_waitcnt vmcnt(4)
	v_cndmask_b32_e64 v188, 0, v188, s[46:47]
	v_bfe_u32 v8, v188, 16, 1
	v_cndmask_b32_e64 v189, 0, v189, s[46:47]
	v_add3_u32 v8, v188, v8, s53
	ds_write_b16_d16_hi v126, v8 offset:43104
	v_bfe_u32 v8, v189, 16, 1
	v_cndmask_b32_e64 v190, 0, v190, s[46:47]
	v_add3_u32 v8, v189, v8, s53
	ds_write_b16_d16_hi v126, v8 offset:43624
	v_bfe_u32 v8, v190, 16, 1
	v_cndmask_b32_e64 v191, 0, v191, s[46:47]
	v_add3_u32 v8, v190, v8, s53
	ds_write_b16_d16_hi v126, v8 offset:44144
	v_bfe_u32 v8, v191, 16, 1
	v_add3_u32 v8, v191, v8, s53
	ds_write_b16_d16_hi v126, v8 offset:44664
	s_and_saveexec_b64 s[48:49], s[8:9]
	s_cbranch_execz .LBB0_172
	s_load_dwordx2 s[54:55], s[0:1], 0xd0
	s_waitcnt lgkmcnt(0)
	v_lshl_add_u64 v[8:9], s[54:55], 0, v[4:5]
	v_lshl_add_u64 v[8:9], v[24:25], 2, v[8:9]
	v_lshl_add_u64 v[8:9], v[96:97], 2, v[8:9]
	v_add_co_u32_e32 v8, vcc, 0x4500000, v8
	s_nop 1
	v_addc_co_u32_e32 v9, vcc, 0, v9, vcc
	global_store_dwordx4 v[8:9], v[188:191], off offset:48
.LBB0_172:
	s_or_b64 exec, exec, s[48:49]
	s_waitcnt vmcnt(3)
	v_cndmask_b32_e64 v196, 0, v196, s[46:47]
	v_bfe_u32 v8, v196, 16, 1
	v_cndmask_b32_e64 v197, 0, v197, s[46:47]
	v_add3_u32 v8, v196, v8, s53
	ds_write_b16_d16_hi v126, v8 offset:45184
	v_bfe_u32 v8, v197, 16, 1
	v_cndmask_b32_e64 v198, 0, v198, s[46:47]
	v_add3_u32 v8, v197, v8, s53
	ds_write_b16_d16_hi v126, v8 offset:45704
	v_bfe_u32 v8, v198, 16, 1
	v_cndmask_b32_e64 v199, 0, v199, s[46:47]
	v_add3_u32 v8, v198, v8, s53
	ds_write_b16_d16_hi v126, v8 offset:46224
	v_bfe_u32 v8, v199, 16, 1
	v_add3_u32 v8, v199, v8, s53
	ds_write_b16_d16_hi v126, v8 offset:46744
	s_and_saveexec_b64 s[48:49], s[8:9]
	s_cbranch_execz .LBB0_174
	s_load_dwordx2 s[54:55], s[0:1], 0xd0
	s_waitcnt lgkmcnt(0)
	v_lshl_add_u64 v[8:9], s[54:55], 0, v[4:5]
	v_lshl_add_u64 v[8:9], v[24:25], 2, v[8:9]
	v_lshl_add_u64 v[8:9], v[96:97], 2, v[8:9]
	v_add_co_u32_e32 v8, vcc, 0x4500000, v8
	s_nop 1
	v_addc_co_u32_e32 v9, vcc, 0, v9, vcc
	global_store_dwordx4 v[8:9], v[196:199], off offset:64
.LBB0_174:
	s_or_b64 exec, exec, s[48:49]
	s_waitcnt vmcnt(2)
	v_cndmask_b32_e64 v200, 0, v200, s[46:47]
	v_bfe_u32 v8, v200, 16, 1
	v_cndmask_b32_e64 v201, 0, v201, s[46:47]
	v_add3_u32 v8, v200, v8, s53
	ds_write_b16_d16_hi v126, v8 offset:47264
	v_bfe_u32 v8, v201, 16, 1
	v_cndmask_b32_e64 v202, 0, v202, s[46:47]
	v_add3_u32 v8, v201, v8, s53
	ds_write_b16_d16_hi v126, v8 offset:47784
	v_bfe_u32 v8, v202, 16, 1
	v_cndmask_b32_e64 v203, 0, v203, s[46:47]
	v_add3_u32 v8, v202, v8, s53
	ds_write_b16_d16_hi v126, v8 offset:48304
	v_bfe_u32 v8, v203, 16, 1
	v_add3_u32 v8, v203, v8, s53
	ds_write_b16_d16_hi v126, v8 offset:48824
	s_and_saveexec_b64 s[48:49], s[8:9]
	s_cbranch_execz .LBB0_176
	s_load_dwordx2 s[54:55], s[0:1], 0xd0
	s_waitcnt lgkmcnt(0)
	v_lshl_add_u64 v[8:9], s[54:55], 0, v[4:5]
	v_lshl_add_u64 v[8:9], v[24:25], 2, v[8:9]
	v_lshl_add_u64 v[8:9], v[96:97], 2, v[8:9]
	v_add_co_u32_e32 v8, vcc, 0x4500000, v8
	s_nop 1
	v_addc_co_u32_e32 v9, vcc, 0, v9, vcc
	global_store_dwordx4 v[8:9], v[200:203], off offset:80
.LBB0_176:
	s_or_b64 exec, exec, s[48:49]
	s_waitcnt vmcnt(1)
	v_cndmask_b32_e64 v204, 0, v204, s[46:47]
	v_bfe_u32 v8, v204, 16, 1
	v_cndmask_b32_e64 v205, 0, v205, s[46:47]
	v_add3_u32 v8, v204, v8, s53
	ds_write_b16_d16_hi v126, v8 offset:49344
	v_bfe_u32 v8, v205, 16, 1
	v_cndmask_b32_e64 v206, 0, v206, s[46:47]
	v_add3_u32 v8, v205, v8, s53
	ds_write_b16_d16_hi v126, v8 offset:49864
	v_bfe_u32 v8, v206, 16, 1
	v_cndmask_b32_e64 v207, 0, v207, s[46:47]
	v_add3_u32 v8, v206, v8, s53
	ds_write_b16_d16_hi v126, v8 offset:50384
	v_bfe_u32 v8, v207, 16, 1
	v_add3_u32 v8, v207, v8, s53
	ds_write_b16_d16_hi v126, v8 offset:50904
	s_and_saveexec_b64 s[48:49], s[8:9]
	s_cbranch_execz .LBB0_178
	s_load_dwordx2 s[54:55], s[0:1], 0xd0
	s_waitcnt lgkmcnt(0)
	v_lshl_add_u64 v[8:9], s[54:55], 0, v[4:5]
	v_lshl_add_u64 v[8:9], v[24:25], 2, v[8:9]
	v_lshl_add_u64 v[8:9], v[96:97], 2, v[8:9]
	v_add_co_u32_e32 v8, vcc, 0x4500000, v8
	s_nop 1
	v_addc_co_u32_e32 v9, vcc, 0, v9, vcc
	global_store_dwordx4 v[8:9], v[204:207], off offset:96
.LBB0_178:
	s_or_b64 exec, exec, s[48:49]
	s_waitcnt vmcnt(0)
	v_cndmask_b32_e64 v208, 0, v208, s[46:47]
	v_bfe_u32 v6, v208, 16, 1
	v_cndmask_b32_e64 v209, 0, v209, s[46:47]
	v_add3_u32 v6, v208, v6, s53
	ds_write_b16_d16_hi v126, v6 offset:51424
	v_bfe_u32 v6, v209, 16, 1
	v_cndmask_b32_e64 v210, 0, v210, s[46:47]
	v_add3_u32 v6, v209, v6, s53
	ds_write_b16_d16_hi v126, v6 offset:51944
	v_bfe_u32 v6, v210, 16, 1
	v_cndmask_b32_e64 v211, 0, v211, s[46:47]
	v_add3_u32 v6, v210, v6, s53
	ds_write_b16_d16_hi v126, v6 offset:52464
	v_bfe_u32 v6, v211, 16, 1
	v_add3_u32 v6, v211, v6, s53
	ds_write_b16_d16_hi v125, v6 offset:36864
	s_and_saveexec_b64 s[46:47], s[8:9]
	s_cbranch_execz .LBB0_180
	s_load_dwordx2 s[8:9], s[0:1], 0xd0
	s_waitcnt lgkmcnt(0)
	v_lshl_add_u64 v[4:5], s[8:9], 0, v[4:5]
	v_lshl_add_u64 v[4:5], v[24:25], 2, v[4:5]
	v_lshl_add_u64 v[4:5], v[96:97], 2, v[4:5]
	v_add_co_u32_e32 v4, vcc, 0x4500000, v4
	s_nop 1
	v_addc_co_u32_e32 v5, vcc, 0, v5, vcc
	global_store_dwordx4 v[4:5], v[208:211], off offset:112

.LBB0_1156:
	s_or_b64 exec, exec, s[18:19]
	s_xor_b64 s[18:19], s[14:15], -1
	s_add_i32 s9, s16, 0xffffc007
	s_and_b64 s[14:15], s[10:11], exec
	s_cselect_b32 s9, s25, s9
	v_mad_i64_i32 v[24:25], s[14:15], s9, v238, v[68:69]
	s_waitcnt lgkmcnt(0)
	global_load_dwordx4 v[100:103], v[66:67], off
	global_load_dwordx4 v[104:107], v[24:25], off
	global_load_dwordx4 v[108:111], v[66:67], off offset:1024
	global_load_dwordx4 v[112:115], v[24:25], off offset:1024
	global_load_dwordx4 v[116:119], v[66:67], off offset:2048
	global_load_dwordx4 v[120:123], v[24:25], off offset:2048
	global_load_dwordx4 v[124:127], v[66:67], off offset:3072
	global_load_dwordx4 v[128:131], v[24:25], off offset:3072
	s_lshl_b32 s94, s8, 11
	s_mov_b32 s8, 4
	s_mov_b64 s[14:15], 0
	s_and_b64 vcc, exec, s[18:19]
	s_waitcnt vmcnt(7)
	v_pk_mul_f32 v[14:15], v[14:15], v[102:103]
	v_pk_mul_f32 v[12:13], v[12:13], v[100:101]
	s_waitcnt vmcnt(6)
	v_pk_add_f32 v[16:17], v[106:107], 1.0 op_sel_hi:[1,0]
	v_pk_add_f32 v[18:19], v[104:105], 1.0 op_sel_hi:[1,0]
	v_pk_mul_f32 v[14:15], v[14:15], v[16:17]
	v_pk_mul_f32 v[12:13], v[12:13], v[18:19]
	v_lshl_add_u64 v[20:21], v[70:71], 0, s[94:95]
	v_cvt_pk_bf16_f32 v12, v12, v13
	v_cvt_pk_bf16_f32 v13, v14, v15
	global_store_dwordx2 v[20:21], v[12:13], off
	s_nop 0
	s_waitcnt vmcnt(6)
	v_pk_mul_f32 v[10:11], v[10:11], v[110:111]
	v_pk_mul_f32 v[8:9], v[8:9], v[108:109]
	s_waitcnt vmcnt(5)
	v_pk_add_f32 v[12:13], v[114:115], 1.0 op_sel_hi:[1,0]
	v_pk_add_f32 v[14:15], v[112:113], 1.0 op_sel_hi:[1,0]
	v_pk_mul_f32 v[10:11], v[10:11], v[12:13]
	v_pk_mul_f32 v[8:9], v[8:9], v[14:15]
	s_nop 0
	v_cvt_pk_bf16_f32 v8, v8, v9
	v_cvt_pk_bf16_f32 v9, v10, v11
	global_store_dwordx2 v[20:21], v[8:9], off offset:512
	s_nop 0
	s_waitcnt vmcnt(5)
	v_pk_mul_f32 v[6:7], v[6:7], v[118:119]
	v_pk_mul_f32 v[4:5], v[4:5], v[116:117]
	s_waitcnt vmcnt(4)
	v_pk_add_f32 v[8:9], v[122:123], 1.0 op_sel_hi:[1,0]
	v_pk_add_f32 v[10:11], v[120:121], 1.0 op_sel_hi:[1,0]
	v_pk_mul_f32 v[6:7], v[6:7], v[8:9]
	v_pk_mul_f32 v[4:5], v[4:5], v[10:11]
	s_nop 0
	v_cvt_pk_bf16_f32 v4, v4, v5
	v_cvt_pk_bf16_f32 v5, v6, v7
	global_store_dwordx2 v[20:21], v[4:5], off offset:1024
	s_nop 0
	s_waitcnt vmcnt(4)
	v_pk_mul_f32 v[2:3], v[2:3], v[126:127]
	v_pk_mul_f32 v[0:1], v[0:1], v[124:125]
	s_waitcnt vmcnt(3)
	v_pk_add_f32 v[4:5], v[130:131], 1.0 op_sel_hi:[1,0]
	v_pk_add_f32 v[6:7], v[128:129], 1.0 op_sel_hi:[1,0]
	v_pk_mul_f32 v[2:3], v[2:3], v[4:5]
	v_pk_mul_f32 v[0:1], v[0:1], v[6:7]
	s_nop 0
	v_cvt_pk_bf16_f32 v0, v0, v1
	v_cvt_pk_bf16_f32 v1, v2, v3
	global_store_dwordx2 v[20:21], v[0:1], off offset:1536
	s_cbranch_vccnz .LBB0_1148

.LBB0_1175:
	s_or_b64 exec, exec, s[22:23]
	s_add_i32 s9, s16, 0xffffc004
	s_and_b64 s[22:23], s[10:11], exec
	s_cselect_b32 s9, s25, s9
	v_mad_i64_i32 v[86:87], s[22:23], s9, v238, v[68:69]
	s_waitcnt lgkmcnt(0)
	global_load_dwordx4 v[100:103], v[66:67], off
	global_load_dwordx4 v[104:107], v[86:87], off
	global_load_dwordx4 v[108:111], v[66:67], off offset:1024
	global_load_dwordx4 v[112:115], v[86:87], off offset:1024
	global_load_dwordx4 v[116:119], v[66:67], off offset:2048
	global_load_dwordx4 v[120:123], v[86:87], off offset:2048
	global_load_dwordx4 v[124:127], v[66:67], off offset:3072
	global_load_dwordx4 v[128:131], v[86:87], off offset:3072
	s_lshl_b32 s94, s16, 11
	s_waitcnt vmcnt(7)
	v_pk_mul_f32 v[62:63], v[62:63], v[102:103]
	v_pk_mul_f32 v[60:61], v[60:61], v[100:101]
	s_waitcnt vmcnt(6)
	v_pk_add_f32 v[78:79], v[106:107], 1.0 op_sel_hi:[1,0]
	v_pk_add_f32 v[80:81], v[104:105], 1.0 op_sel_hi:[1,0]
	v_pk_mul_f32 v[62:63], v[62:63], v[78:79]
	v_pk_mul_f32 v[60:61], v[60:61], v[80:81]
	v_lshl_add_u64 v[82:83], v[70:71], 0, s[94:95]
	v_cvt_pk_bf16_f32 v60, v60, v61
	v_cvt_pk_bf16_f32 v61, v62, v63
	global_store_dwordx2 v[82:83], v[60:61], off
	s_nop 0
	s_waitcnt vmcnt(6)
	v_pk_mul_f32 v[58:59], v[58:59], v[110:111]
	v_pk_mul_f32 v[56:57], v[56:57], v[108:109]
	s_waitcnt vmcnt(5)
	v_pk_add_f32 v[60:61], v[114:115], 1.0 op_sel_hi:[1,0]
	v_pk_add_f32 v[62:63], v[112:113], 1.0 op_sel_hi:[1,0]
	v_pk_mul_f32 v[58:59], v[58:59], v[60:61]
	v_pk_mul_f32 v[56:57], v[56:57], v[62:63]
	s_nop 0
	v_cvt_pk_bf16_f32 v56, v56, v57
	v_cvt_pk_bf16_f32 v57, v58, v59
	global_store_dwordx2 v[82:83], v[56:57], off offset:512
	s_nop 0
	s_waitcnt vmcnt(5)
	v_pk_mul_f32 v[54:55], v[54:55], v[118:119]
	v_pk_mul_f32 v[52:53], v[52:53], v[116:117]
	s_waitcnt vmcnt(4)
	v_pk_add_f32 v[56:57], v[122:123], 1.0 op_sel_hi:[1,0]
	v_pk_add_f32 v[58:59], v[120:121], 1.0 op_sel_hi:[1,0]
	v_pk_mul_f32 v[54:55], v[54:55], v[56:57]
	v_pk_mul_f32 v[52:53], v[52:53], v[58:59]
	s_nop 0
	v_cvt_pk_bf16_f32 v52, v52, v53
	v_cvt_pk_bf16_f32 v53, v54, v55
	global_store_dwordx2 v[82:83], v[52:53], off offset:1024
	s_nop 0
	s_waitcnt vmcnt(4)
	v_pk_mul_f32 v[50:51], v[50:51], v[126:127]
	v_pk_mul_f32 v[48:49], v[48:49], v[124:125]
	s_waitcnt vmcnt(3)
	v_pk_add_f32 v[52:53], v[130:131], 1.0 op_sel_hi:[1,0]
	v_pk_add_f32 v[54:55], v[128:129], 1.0 op_sel_hi:[1,0]
	v_pk_mul_f32 v[50:51], v[50:51], v[52:53]
	v_pk_mul_f32 v[48:49], v[48:49], v[54:55]
	s_nop 0
	v_cvt_pk_bf16_f32 v48, v48, v49
	v_cvt_pk_bf16_f32 v49, v50, v51
	global_store_dwordx2 v[82:83], v[48:49], off offset:1536
	v_mul_f32_e32 v48, v45, v45
	v_mul_f32_e32 v49, v41, v41
	v_fmac_f32_e32 v48, v44, v44
	v_fmac_f32_e32 v49, v40, v40
	v_fmac_f32_e32 v48, v46, v46
	v_fmac_f32_e32 v49, v42, v42
	v_fmac_f32_e32 v48, v47, v47
	v_fmac_f32_e32 v49, v43, v43
	v_add_f32_e32 v48, v48, v49
	v_mul_f32_e32 v49, v37, v37
	v_fmac_f32_e32 v49, v36, v36
	v_fmac_f32_e32 v49, v38, v38
	v_fmac_f32_e32 v49, v39, v39
	v_add_f32_e32 v48, v48, v49
	v_mul_f32_e32 v49, v33, v33
	v_fmac_f32_e32 v49, v32, v32
	v_fmac_f32_e32 v49, v34, v34
	v_fmac_f32_e32 v49, v35, v35
	v_add_f32_e32 v48, v48, v49
	ds_bpermute_b32 v49, v65, v48
	s_waitcnt lgkmcnt(0)
	v_add_f32_e32 v48, v48, v49
	ds_bpermute_b32 v49, v72, v48
	s_waitcnt lgkmcnt(0)
	v_add_f32_e32 v48, v48, v49
	ds_bpermute_b32 v49, v73, v48
	s_waitcnt lgkmcnt(0)
	v_add_f32_e32 v48, v48, v49
	ds_bpermute_b32 v49, v74, v48
	s_waitcnt lgkmcnt(0)
	v_add_f32_e32 v48, v48, v49
	ds_bpermute_b32 v49, v75, v48
	s_waitcnt lgkmcnt(0)
	v_add_f32_e32 v48, v48, v49
	ds_bpermute_b32 v49, v76, v48
	s_and_saveexec_b64 s[22:23], s[6:7]
	s_cbranch_execz .LBB0_1177
	s_mov_b32 s21, s95
	s_lshl_b64 s[26:27], s[20:21], 2
	s_add_u32 s26, s76, s26
	s_addc_u32 s27, s77, s27
	s_waitcnt lgkmcnt(0)
	v_add_f32_e32 v48, v48, v49
	global_store_dword v193, v48, s[26:27]
.LBB0_1177:
	s_or_b64 exec, exec, s[22:23]
	s_add_i32 s9, s16, 0xffffc005
	s_and_b64 s[22:23], s[10:11], exec
	s_cselect_b32 s9, s25, s9
	v_mad_i64_i32 v[56:57], s[22:23], s9, v238, v[68:69]
	s_waitcnt lgkmcnt(0)
	global_load_dwordx4 v[100:103], v[66:67], off
	global_load_dwordx4 v[104:107], v[56:57], off
	global_load_dwordx4 v[108:111], v[66:67], off offset:1024
	global_load_dwordx4 v[112:115], v[56:57], off offset:1024
	global_load_dwordx4 v[116:119], v[66:67], off offset:2048
	global_load_dwordx4 v[120:123], v[56:57], off offset:2048
	global_load_dwordx4 v[124:127], v[66:67], off offset:3072
	global_load_dwordx4 v[128:131], v[56:57], off offset:3072
	s_lshl_b32 s94, s20, 11
	s_waitcnt vmcnt(7)
	v_pk_mul_f32 v[46:47], v[46:47], v[102:103]
	v_pk_mul_f32 v[44:45], v[44:45], v[100:101]
	s_waitcnt vmcnt(6)
	v_pk_add_f32 v[48:49], v[106:107], 1.0 op_sel_hi:[1,0]
	v_pk_add_f32 v[50:51], v[104:105], 1.0 op_sel_hi:[1,0]
	v_pk_mul_f32 v[46:47], v[46:47], v[48:49]
	v_pk_mul_f32 v[44:45], v[44:45], v[50:51]
	v_lshl_add_u64 v[52:53], v[70:71], 0, s[94:95]
	v_cvt_pk_bf16_f32 v44, v44, v45
	v_cvt_pk_bf16_f32 v45, v46, v47
	global_store_dwordx2 v[52:53], v[44:45], off
	s_nop 0
	s_waitcnt vmcnt(6)
	v_pk_mul_f32 v[42:43], v[42:43], v[110:111]
	v_pk_mul_f32 v[40:41], v[40:41], v[108:109]
	s_waitcnt vmcnt(5)
	v_pk_add_f32 v[44:45], v[114:115], 1.0 op_sel_hi:[1,0]
	v_pk_add_f32 v[46:47], v[112:113], 1.0 op_sel_hi:[1,0]
	v_pk_mul_f32 v[42:43], v[42:43], v[44:45]
	v_pk_mul_f32 v[40:41], v[40:41], v[46:47]
	s_nop 0
	v_cvt_pk_bf16_f32 v40, v40, v41
	v_cvt_pk_bf16_f32 v41, v42, v43
	global_store_dwordx2 v[52:53], v[40:41], off offset:512
	s_nop 0
	s_waitcnt vmcnt(5)
	v_pk_mul_f32 v[38:39], v[38:39], v[118:119]
	v_pk_mul_f32 v[36:37], v[36:37], v[116:117]
	s_waitcnt vmcnt(4)
	v_pk_add_f32 v[40:41], v[122:123], 1.0 op_sel_hi:[1,0]
	v_pk_add_f32 v[42:43], v[120:121], 1.0 op_sel_hi:[1,0]
	v_pk_mul_f32 v[38:39], v[38:39], v[40:41]
	v_pk_mul_f32 v[36:37], v[36:37], v[42:43]
	s_nop 0
	v_cvt_pk_bf16_f32 v36, v36, v37
	v_cvt_pk_bf16_f32 v37, v38, v39
	global_store_dwordx2 v[52:53], v[36:37], off offset:1024
	s_nop 0
	s_waitcnt vmcnt(4)
	v_pk_mul_f32 v[34:35], v[34:35], v[126:127]
	v_pk_mul_f32 v[32:33], v[32:33], v[124:125]
	s_waitcnt vmcnt(3)
	v_pk_add_f32 v[36:37], v[130:131], 1.0 op_sel_hi:[1,0]
	v_pk_add_f32 v[38:39], v[128:129], 1.0 op_sel_hi:[1,0]
	v_pk_mul_f32 v[34:35], v[34:35], v[36:37]
	v_pk_mul_f32 v[32:33], v[32:33], v[38:39]
	s_nop 0
	v_cvt_pk_bf16_f32 v32, v32, v33
	v_cvt_pk_bf16_f32 v33, v34, v35
	global_store_dwordx2 v[52:53], v[32:33], off offset:1536
	v_mul_f32_e32 v32, v29, v29
	v_mul_f32_e32 v33, v25, v25
	v_fmac_f32_e32 v32, v28, v28
	v_fmac_f32_e32 v33, v24, v24
	v_fmac_f32_e32 v32, v30, v30
	v_fmac_f32_e32 v33, v26, v26
	v_fmac_f32_e32 v32, v31, v31
	v_fmac_f32_e32 v33, v27, v27
	v_add_f32_e32 v32, v32, v33
	v_mul_f32_e32 v33, v21, v21
	v_fmac_f32_e32 v33, v20, v20
	v_fmac_f32_e32 v33, v22, v22
	v_fmac_f32_e32 v33, v23, v23
	v_add_f32_e32 v32, v32, v33
	v_mul_f32_e32 v33, v17, v17
	v_fmac_f32_e32 v33, v16, v16
	v_fmac_f32_e32 v33, v18, v18
	v_fmac_f32_e32 v33, v19, v19
	v_add_f32_e32 v32, v32, v33
	ds_bpermute_b32 v33, v65, v32
	s_waitcnt lgkmcnt(0)
	v_add_f32_e32 v32, v32, v33
	ds_bpermute_b32 v33, v72, v32
	s_waitcnt lgkmcnt(0)
	v_add_f32_e32 v32, v32, v33
	ds_bpermute_b32 v33, v73, v32
	s_waitcnt lgkmcnt(0)
	v_add_f32_e32 v32, v32, v33
	ds_bpermute_b32 v33, v74, v32
	s_waitcnt lgkmcnt(0)
	v_add_f32_e32 v32, v32, v33
	ds_bpermute_b32 v33, v75, v32
	s_waitcnt lgkmcnt(0)
	v_add_f32_e32 v32, v32, v33
	ds_bpermute_b32 v33, v76, v32
	s_and_saveexec_b64 s[20:21], s[6:7]
	s_cbranch_execz .LBB0_1179
	s_mov_b32 s19, s95
	s_lshl_b64 s[22:23], s[18:19], 2
	s_add_u32 s22, s76, s22
	s_addc_u32 s23, s77, s23
	s_waitcnt lgkmcnt(0)
	v_add_f32_e32 v32, v32, v33
	global_store_dword v193, v32, s[22:23]
.LBB0_1179:
	s_or_b64 exec, exec, s[20:21]
	s_add_i32 s9, s16, 0xffffc006
	s_and_b64 s[20:21], s[10:11], exec
	s_cselect_b32 s9, s25, s9
	v_mad_i64_i32 v[40:41], s[20:21], s9, v238, v[68:69]
	s_waitcnt lgkmcnt(0)
	global_load_dwordx4 v[100:103], v[66:67], off
	global_load_dwordx4 v[104:107], v[40:41], off
	global_load_dwordx4 v[108:111], v[66:67], off offset:1024
	global_load_dwordx4 v[112:115], v[40:41], off offset:1024
	global_load_dwordx4 v[116:119], v[66:67], off offset:2048
	global_load_dwordx4 v[120:123], v[40:41], off offset:2048
	global_load_dwordx4 v[124:127], v[66:67], off offset:3072
	global_load_dwordx4 v[128:131], v[40:41], off offset:3072
	s_lshl_b32 s94, s18, 11
	s_waitcnt vmcnt(7)
	v_pk_mul_f32 v[30:31], v[30:31], v[102:103]
	v_pk_mul_f32 v[28:29], v[28:29], v[100:101]
	s_waitcnt vmcnt(6)
	v_pk_add_f32 v[32:33], v[106:107], 1.0 op_sel_hi:[1,0]
	v_pk_add_f32 v[34:35], v[104:105], 1.0 op_sel_hi:[1,0]
	v_pk_mul_f32 v[30:31], v[30:31], v[32:33]
	v_pk_mul_f32 v[28:29], v[28:29], v[34:35]
	v_lshl_add_u64 v[36:37], v[70:71], 0, s[94:95]
	v_cvt_pk_bf16_f32 v28, v28, v29
	v_cvt_pk_bf16_f32 v29, v30, v31
	global_store_dwordx2 v[36:37], v[28:29], off
	s_nop 0
	s_waitcnt vmcnt(6)
	v_pk_mul_f32 v[26:27], v[26:27], v[110:111]
	v_pk_mul_f32 v[24:25], v[24:25], v[108:109]
	s_waitcnt vmcnt(5)
	v_pk_add_f32 v[28:29], v[114:115], 1.0 op_sel_hi:[1,0]
	v_pk_add_f32 v[30:31], v[112:113], 1.0 op_sel_hi:[1,0]
	v_pk_mul_f32 v[26:27], v[26:27], v[28:29]
	v_pk_mul_f32 v[24:25], v[24:25], v[30:31]
	s_nop 0
	v_cvt_pk_bf16_f32 v24, v24, v25
	v_cvt_pk_bf16_f32 v25, v26, v27
	global_store_dwordx2 v[36:37], v[24:25], off offset:512
	s_nop 0
	s_waitcnt vmcnt(5)
	v_pk_mul_f32 v[22:23], v[22:23], v[118:119]
	v_pk_mul_f32 v[20:21], v[20:21], v[116:117]
	s_waitcnt vmcnt(4)
	v_pk_add_f32 v[24:25], v[122:123], 1.0 op_sel_hi:[1,0]
	v_pk_add_f32 v[26:27], v[120:121], 1.0 op_sel_hi:[1,0]
	v_pk_mul_f32 v[22:23], v[22:23], v[24:25]
	v_pk_mul_f32 v[20:21], v[20:21], v[26:27]
	s_nop 0
	v_cvt_pk_bf16_f32 v20, v20, v21
	v_cvt_pk_bf16_f32 v21, v22, v23
	global_store_dwordx2 v[36:37], v[20:21], off offset:1024
	s_nop 0
	s_waitcnt vmcnt(4)
	v_pk_mul_f32 v[18:19], v[18:19], v[126:127]
	v_pk_mul_f32 v[16:17], v[16:17], v[124:125]
	s_waitcnt vmcnt(3)
	v_pk_add_f32 v[20:21], v[130:131], 1.0 op_sel_hi:[1,0]
	v_pk_add_f32 v[22:23], v[128:129], 1.0 op_sel_hi:[1,0]
	v_pk_mul_f32 v[18:19], v[18:19], v[20:21]
	v_pk_mul_f32 v[16:17], v[16:17], v[22:23]
	s_nop 0
	v_cvt_pk_bf16_f32 v16, v16, v17
	v_cvt_pk_bf16_f32 v17, v18, v19
	global_store_dwordx2 v[36:37], v[16:17], off offset:1536
	v_mul_f32_e32 v16, v13, v13
	v_mul_f32_e32 v17, v9, v9
	v_fmac_f32_e32 v16, v12, v12
	v_fmac_f32_e32 v17, v8, v8
	v_fmac_f32_e32 v16, v14, v14
	v_fmac_f32_e32 v17, v10, v10
	v_fmac_f32_e32 v16, v15, v15
	v_fmac_f32_e32 v17, v11, v11
	v_add_f32_e32 v16, v16, v17
	v_mul_f32_e32 v17, v5, v5
	v_fmac_f32_e32 v17, v4, v4
	v_fmac_f32_e32 v17, v6, v6
	v_fmac_f32_e32 v17, v7, v7
	v_add_f32_e32 v16, v16, v17
	v_mul_f32_e32 v17, v1, v1
	v_fmac_f32_e32 v17, v0, v0
	v_fmac_f32_e32 v17, v2, v2
	v_fmac_f32_e32 v17, v3, v3
	v_add_f32_e32 v16, v16, v17
	ds_bpermute_b32 v17, v65, v16
	s_waitcnt lgkmcnt(0)
	v_add_f32_e32 v16, v16, v17
	ds_bpermute_b32 v17, v72, v16
	s_waitcnt lgkmcnt(0)
	v_add_f32_e32 v16, v16, v17
	ds_bpermute_b32 v17, v73, v16
	s_waitcnt lgkmcnt(0)
	v_add_f32_e32 v16, v16, v17
	ds_bpermute_b32 v17, v74, v16
	s_waitcnt lgkmcnt(0)
	v_add_f32_e32 v16, v16, v17
	ds_bpermute_b32 v17, v75, v16
	s_waitcnt lgkmcnt(0)
	v_add_f32_e32 v16, v16, v17
	ds_bpermute_b32 v17, v76, v16
	s_and_saveexec_b64 s[18:19], s[6:7]
	s_cbranch_execz .LBB0_1156
	s_mov_b32 s9, s95
	s_lshl_b64 s[20:21], s[8:9], 2
	s_add_u32 s20, s76, s20
	s_addc_u32 s21, s77, s21
	s_waitcnt lgkmcnt(0)
	v_add_f32_e32 v16, v16, v17
	global_store_dword v193, v16, s[20:21]
	s_branch .LBB0_1156

.LBB0_1188:
	s_or_b64 exec, exec, s[10:11]
	v_cvt_f32_u32_e32 v4, v2
	s_waitcnt vmcnt(0)
	buffer_inv sc1
	v_readfirstlane_b32 s8, v3
	v_sub_u32_e32 v3, 0, v2
	v_rcp_iflag_f32_e32 v4, v4
	v_add_u32_e32 v5, s8, v1
	v_mul_f32_e32 v4, 0x4f7ffffe, v4
	v_cvt_u32_f32_e32 v4, v4
	v_mul_lo_u32 v1, v3, v4
	v_mul_hi_u32 v1, v4, v1
	v_add_u32_e32 v1, v4, v1
	v_mul_hi_u32 v1, v5, v1
	v_mul_lo_u32 v3, v1, v2
	v_sub_u32_e32 v3, v5, v3
	v_add_u32_e32 v4, 1, v1
	v_cmp_ge_u32_e32 vcc, v3, v2
	s_nop 1
	v_cndmask_b32_e32 v1, v1, v4, vcc
	v_sub_u32_e32 v4, v3, v2
	v_cndmask_b32_e32 v3, v3, v4, vcc
	v_add_u32_e32 v4, 1, v1
	v_cmp_ge_u32_e32 vcc, v3, v2
	v_add_u32_e32 v3, 1, v5
	s_nop 0
	v_cndmask_b32_e32 v1, v1, v4, vcc
	v_mul_lo_u32 v4, v2, v1
	v_add_u32_e32 v2, v4, v2
	v_cmp_ne_u32_e32 vcc, v3, v2
	s_and_saveexec_b64 s[8:9], vcc
	s_xor_b64 s[8:9], exec, s[8:9]
	s_cbranch_execz .LBB0_1202
	s_waitcnt lgkmcnt(0)
	global_load_dword v0, v234, s[6:7] offset:1024 sc1
	s_add_u32 s14, s6, 0x2400
	s_addc_u32 s15, s7, 0
	s_waitcnt vmcnt(0)
	v_cmp_eq_u32_e32 vcc, v0, v1
	s_and_saveexec_b64 s[10:11], vcc
	s_cbranch_execz .LBB0_1201
	s_add_u32 s12, s2, 0x1b069200
	s_addc_u32 s13, s3, 0
	s_mov_b32 s26, 1
	s_mov_b64 s[16:17], 0
	s_branch .LBB0_1192

.LBB0_1201:
	s_or_b64 exec, exec, s[10:11]
	s_waitcnt vmcnt(0)
	s_waitcnt vmcnt(0)

.LBB0_1219:
	s_or_b64 exec, exec, s[2:3]
	s_mov_b64 s[2:3], exec
	v_mbcnt_lo_u32_b32 v0, s2, 0
	v_mbcnt_hi_u32_b32 v0, s3, v0
	v_cmp_eq_u32_e32 vcc, 0, v0
	s_waitcnt vmcnt(0)
	s_and_saveexec_b64 s[8:9], vcc
	s_cbranch_execz .LBB0_1221
	s_bcnt1_i32_b64 s2, s[2:3]
	v_mov_b32_e32 v0, s2
	global_atomic_add v234, v0, s[6:7] offset:1024
